# E5 nsa selected-block stream: K/V tiles that none of the block's 32 tokens selected are no longer loaded or staged (union mask in an SGPR)
# speedup vs baseline: 1.0063x; 1.0063x over previous
.LBB0_912:
	v_cmp_eq_u32_e32 vcc, 0, v35
	s_and_saveexec_b64 s[2:3], vcc
	v_lshlrev_b32_e32 v34, 2, v34
	ds_write_b32 v34, v44 offset:20608
	s_or_b64 exec, exec, s[2:3]
	s_mov_b32 s41, s77
	s_lshl_b64 s[2:3], s[40:41], 8
	s_add_u32 s22, s9, s2
	s_addc_u32 s23, s10, s3
	s_lshl_b32 s17, s17, 7
	s_add_u32 s22, s22, s17
	s_addc_u32 s23, s23, 0
	s_lshl_b64 s[38:39], s[76:77], 18
	s_add_u32 s40, s11, s38
	s_addc_u32 s41, s12, s39
	v_lshlrev_b32_e32 v34, 2, v91
	s_waitcnt vmcnt(0)
	v_mov_b32_e32 v64, v206
	s_cmp_lt_u32 s14, 64
	s_waitcnt lgkmcnt(0)
	s_setprio 0
	s_barrier
	ds_read_b32 v171, v34 offset:20608
	s_cselect_b32 s17, 0, 64
	v_ashrrev_i32_e32 v50, 3, v64
	v_lshlrev_b32_e32 v34, 3, v64
	v_add_u32_e32 v42, 32, v50
	v_add_u32_e32 v60, s17, v50
	v_and_b32_e32 v36, 56, v34
	v_ashrrev_i32_e32 v51, 31, v50
	v_ashrrev_i32_e32 v43, 31, v42
	v_ashrrev_i32_e32 v61, 31, v60
	v_lshlrev_b64 v[52:53], 8, v[50:51]
	v_lshlrev_b32_e32 v172, 1, v36
	v_lshlrev_b64 v[36:37], 8, v[42:43]
	v_lshlrev_b64 v[54:55], 12, v[50:51]
	v_lshlrev_b64 v[42:43], 12, v[42:43]
	v_lshlrev_b64 v[60:61], 8, v[60:61]
	v_lshl_add_u64 v[34:35], s[22:23], 0, v[52:53]
	v_mov_b32_e32 v173, v1
	v_lshl_add_u64 v[36:37], s[22:23], 0, v[36:37]
	v_lshl_add_u64 v[56:57], s[40:41], 0, v[54:55]
	v_lshl_add_u64 v[58:59], s[40:41], 0, v[42:43]
	v_lshl_add_u64 v[60:61], s[22:23], 0, v[60:61]
	s_lshl_b32 s76, s17, 1
	v_lshl_add_u64 v[34:35], v[34:35], 0, v[172:173]
	v_lshl_add_u64 v[38:39], v[36:37], 0, v[172:173]
	v_lshl_add_u64 v[44:45], v[56:57], 0, v[172:173]
	v_lshl_add_u64 v[46:47], v[58:59], 0, v[172:173]
	v_lshl_add_u64 v[60:61], v[60:61], 0, v[172:173]
	s_movk_i32 s22, 0x2000
	v_lshl_add_u64 v[56:57], v[56:57], 0, s[76:77]
	s_waitcnt lgkmcnt(0)
	v_readlane_b32 s92, v171, 0
	v_readlane_b32 vcc_lo, v171, 1
	s_or_b32 s92, s92, vcc_lo
	v_readlane_b32 vcc_lo, v171, 2
	s_or_b32 s92, s92, vcc_lo
	v_readlane_b32 vcc_lo, v171, 3
	s_or_b32 s92, s92, vcc_lo
	v_readlane_b32 vcc_lo, v171, 4
	s_or_b32 s92, s92, vcc_lo
	v_readlane_b32 vcc_lo, v171, 5
	s_or_b32 s92, s92, vcc_lo
	v_readlane_b32 vcc_lo, v171, 6
	s_or_b32 s92, s92, vcc_lo
	v_readlane_b32 vcc_lo, v171, 7
	s_or_b32 s92, s92, vcc_lo
	v_readlane_b32 vcc_lo, v171, 8
	s_or_b32 s92, s92, vcc_lo
	v_readlane_b32 vcc_lo, v171, 9
	s_or_b32 s92, s92, vcc_lo
	v_readlane_b32 vcc_lo, v171, 10
	s_or_b32 s92, s92, vcc_lo
	v_readlane_b32 vcc_lo, v171, 11
	s_or_b32 s92, s92, vcc_lo
	v_readlane_b32 vcc_lo, v171, 12
	s_or_b32 s92, s92, vcc_lo
	v_readlane_b32 vcc_lo, v171, 13
	s_or_b32 s92, s92, vcc_lo
	v_readlane_b32 vcc_lo, v171, 14
	s_or_b32 s92, s92, vcc_lo
	v_readlane_b32 vcc_lo, v171, 15
	s_or_b32 s92, s92, vcc_lo
	v_readlane_b32 vcc_lo, v171, 16
	s_or_b32 s92, s92, vcc_lo
	v_readlane_b32 vcc_lo, v171, 17
	s_or_b32 s92, s92, vcc_lo
	v_readlane_b32 vcc_lo, v171, 18
	s_or_b32 s92, s92, vcc_lo
	v_readlane_b32 vcc_lo, v171, 19
	s_or_b32 s92, s92, vcc_lo
	v_readlane_b32 vcc_lo, v171, 20
	s_or_b32 s92, s92, vcc_lo
	v_readlane_b32 vcc_lo, v171, 21
	s_or_b32 s92, s92, vcc_lo
	v_readlane_b32 vcc_lo, v171, 22
	s_or_b32 s92, s92, vcc_lo
	v_readlane_b32 vcc_lo, v171, 23
	s_or_b32 s92, s92, vcc_lo
	v_readlane_b32 vcc_lo, v171, 24
	s_or_b32 s92, s92, vcc_lo
	v_readlane_b32 vcc_lo, v171, 25
	s_or_b32 s92, s92, vcc_lo
	v_readlane_b32 vcc_lo, v171, 26
	s_or_b32 s92, s92, vcc_lo
	v_readlane_b32 vcc_lo, v171, 27
	s_or_b32 s92, s92, vcc_lo
	v_readlane_b32 vcc_lo, v171, 28
	s_or_b32 s92, s92, vcc_lo
	v_readlane_b32 vcc_lo, v171, 29
	s_or_b32 s92, s92, vcc_lo
	v_readlane_b32 vcc_lo, v171, 30
	s_or_b32 s92, s92, vcc_lo
	v_readlane_b32 vcc_lo, v171, 31
	s_or_b32 s92, s92, vcc_lo
	s_setprio 0
	s_barrier
	global_load_dwordx4 v[34:37], v[34:35], off
	s_nop 0
	global_load_dwordx4 v[38:41], v[38:39], off
	s_nop 0
	global_load_dwordx4 v[42:45], v[44:45], off
	s_nop 0
	global_load_dwordx4 v[46:49], v[46:47], off
	v_add_co_u32_e32 v62, vcc, s22, v60
	v_lshl_add_u64 v[56:57], v[56:57], 0, v[172:173]
	v_lshl_add_u64 v[58:59], v[58:59], 0, s[76:77]
	v_addc_co_u32_e32 v63, vcc, 0, v61, vcc
	v_lshl_add_u64 v[58:59], v[58:59], 0, v[172:173]
	global_load_dwordx4 v[154:157], v[56:57], off
	global_load_dwordx4 v[158:161], v[58:59], off
	global_load_dwordx4 v[146:149], v[60:61], off
	global_load_dwordx4 v[150:153], v[62:63], off
	s_or_b32 s17, s14, 31
	s_add_u32 s22, s18, s38
	s_addc_u32 s23, s19, s39
	s_lshl_b32 s16, s16, 1
	s_and_b32 s16, s16, 0x80
	s_add_u32 s16, s18, s16
	v_mul_lo_u32 v186, v50, s21
	v_lshl_add_u64 v[176:177], s[22:23], 0, v[54:55]
	s_addc_u32 s22, s19, 0
	v_lshrrev_b32_e32 v51, 2, v90
	v_add_u32_e32 v50, v186, v172
	s_add_u32 s2, s16, s2
	v_or_b32_e32 v56, 32, v92
	v_add_u32_e32 v57, s14, v91
	v_and_b32_e32 v183, 8, v51
	v_and_b32_e32 v51, 7, v64
	s_addc_u32 s3, s22, s3
	v_mul_u32_u24_e32 v184, 0x90, v56
	v_sub_u32_e32 v185, v57, v166
	v_lshlrev_b32_e32 v174, 4, v51
	v_lshl_add_u64 v[180:181], s[2:3], 0, v[52:53]
	v_mul_u32_u24_e32 v173, 0x90, v93
	v_mul_u32_u24_e32 v182, 0x90, v91
	v_mov_b32_e32 v175, v1
	v_mov_b32_e32 v187, 0
	v_mov_b32_e32 v188, 0
	v_mov_b32_e32 v189, 0xff800000
	s_mov_b32 s16, 63
	s_mov_b32 s22, 0
	s_waitcnt vmcnt(7)
	ds_write_b128 v50, v[34:37]
	s_waitcnt vmcnt(6)
	ds_write_b128 v50, v[38:41] offset:4608
	s_waitcnt vmcnt(5)
	ds_write_b128 v50, v[42:45] offset:9216
	s_waitcnt vmcnt(4)
	ds_write_b128 v50, v[46:49] offset:13824
	v_mov_b32_e32 v48, v1
	v_mov_b32_e32 v49, v1
	v_mov_b32_e32 v34, v1
	v_mov_b32_e32 v35, v1
	v_mov_b32_e32 v36, v1
	v_mov_b32_e32 v37, v1
	v_mov_b32_e32 v38, v1
	v_mov_b32_e32 v39, v1
	v_mov_b32_e32 v40, v1
	v_mov_b32_e32 v41, v1
	v_mov_b32_e32 v42, v1
	v_mov_b32_e32 v43, v1
	v_mov_b32_e32 v44, v1
	v_mov_b32_e32 v45, v1
	v_mov_b32_e32 v46, v1
	v_mov_b32_e32 v47, v1
	v_mov_b64_e32 v[64:65], v[48:49]
	v_mov_b64_e32 v[62:63], v[46:47]
	v_mov_b64_e32 v[60:61], v[44:45]
	v_mov_b64_e32 v[58:59], v[42:43]
	v_mov_b64_e32 v[56:57], v[40:41]
	v_mov_b64_e32 v[54:55], v[38:39]
	v_mov_b64_e32 v[52:53], v[36:37]
	v_mov_b64_e32 v[50:51], v[34:35]
	s_waitcnt lgkmcnt(0)
	s_setprio 0
	s_barrier
	s_and_b32 s23, s22, 1
	s_cmp_ge_u32 s22, s15
	s_cbranch_scc1 .LBB0_917
	s_branch .LBB0_916

.LBB0_916:
	s_add_i32 s2, s22, 1
	s_bitcmp0_b32 s92, s2
	s_cbranch_scc1 .LBB0_917
	s_xor_b32 s2, s23, 1
	s_mulk_i32 s2, 0x4800
	v_add3_u32 v66, v186, s2, v172
	s_waitcnt vmcnt(1)
	ds_write_b128 v66, v[146:149]
	s_waitcnt vmcnt(0)
	ds_write_b128 v66, v[150:153] offset:4608
	ds_write_b128 v66, v[154:157] offset:9216
	ds_write_b128 v66, v[158:161] offset:13824
.LBB0_917:
	s_add_i32 s2, s22, 2
	s_cmp_gt_u32 s2, s15
	s_cbranch_scc1 .LBB0_919
	s_bitcmp0_b32 s92, s2
	s_cbranch_scc1 .LBB0_919
	v_lshl_add_u64 v[66:67], v[180:181], 0, v[174:175]
	v_add_co_u32_e32 v68, vcc, 0x6c08000, v66
	s_nop 1
	v_addc_co_u32_e32 v69, vcc, 0, v67, vcc
	v_add_co_u32_e32 v66, vcc, 0x6c0a000, v66
	s_nop 1
	v_addc_co_u32_e32 v67, vcc, 0, v67, vcc
	global_load_dwordx4 v[146:149], v[68:69], off
	global_load_dwordx4 v[150:153], v[66:67], off
	v_lshl_add_u64 v[66:67], v[176:177], 0, v[174:175]
	v_add_co_u32_e32 v68, vcc, 0x7000000, v66
	s_nop 1
	v_addc_co_u32_e32 v69, vcc, 0, v67, vcc
	v_add_co_u32_e32 v66, vcc, 0x7020000, v66
	s_nop 1
	v_addc_co_u32_e32 v67, vcc, 0, v67, vcc
	global_load_dwordx4 v[154:157], v[68:69], off offset:256
	global_load_dwordx4 v[158:161], v[66:67], off offset:256

.LBB0_942:
	s_mov_b32 s92, 0xc4a0000
	s_waitcnt vmcnt(0)
	s_setprio 0
	s_barrier
	s_mov_b64 s[18:19], exec
	v_readlane_b32 s2, v243, 1
	v_readlane_b32 s3, v243, 2
	s_and_b64 s[2:3], s[18:19], s[2:3]
	v_readlane_b32 s12, v242, 16
	s_mov_b64 exec, s[2:3]
	s_cbranch_execz .LBB0_994
	s_waitcnt vmcnt(0) expcnt(0) lgkmcnt(0)
	ds_read_b32 v3, v1 offset:55296
	ds_read_b32 v2, v1 offset:55300
	s_waitcnt lgkmcnt(1)
	v_cmp_ne_u32_e32 vcc, 0, v3
	s_cbranch_vccnz .LBB0_958
	s_mov_b32 s4, 1
	s_branch .LBB0_946
